# differential-attention tile loop: softmax row sums and in-place exp2 arguments use packed f32 VALU ops (v_pk_add_f32 / v_pk_fma_f32) instead of scalar chains
# speedup vs baseline: 1.0132x; 1.0132x over previous
.LBB0_1085:
	ds_read_b128 v[64:67], v181 offset:40960
	ds_read_b128 v[68:71], v181 offset:45056
	v_exp_f32_e32 v194, v136
	v_pk_add_f32 v[190:191], v[144:145], v[146:147]
	v_pk_add_f32 v[190:191], v[190:191], v[148:149]
	s_waitcnt lgkmcnt(1)
	v_mfma_f32_32x32x16_bf16 v[80:95], v[64:67], v[108:111], 0
	v_pk_add_f32 v[190:191], v[190:191], v[150:151]
	v_pk_add_f32 v[190:191], v[190:191], v[160:161]
	ds_read_b128 v[198:201], v187 offset:40960
	ds_read_b128 v[202:205], v187 offset:45056
	v_pk_add_f32 v[190:191], v[190:191], v[162:163]
	v_pk_add_f32 v[190:191], v[190:191], v[142:143]
	s_waitcnt lgkmcnt(2)
	v_mfma_f32_32x32x16_bf16 v[64:79], v[68:71], v[108:111], 0
	v_exp_f32_e32 v141, v138
	v_exp_f32_e32 v192, v139
	s_waitcnt lgkmcnt(1)
	v_mfma_f32_32x32x16_bf16 v[80:95], v[198:201], v[100:103], v[80:95]
	v_exp_f32_e32 v195, v137
	v_exp_f32_e32 v132, v132
	v_exp_f32_e32 v133, v133
	v_pk_add_f32 v[190:191], v[190:191], v[192:193]
	s_waitcnt lgkmcnt(0)
	v_mfma_f32_32x32x16_bf16 v[64:79], v[202:205], v[100:103], v[64:79]
	ds_read_b128 v[198:201], v188 offset:40960
	ds_read_b128 v[202:205], v188 offset:45056
	v_exp_f32_e32 v128, v128
	v_exp_f32_e32 v129, v129
	v_pk_add_f32 v[190:191], v[190:191], v[194:195]
	v_exp_f32_e32 v126, v126
	s_waitcnt lgkmcnt(1)
	v_mfma_f32_32x32x16_bf16 v[80:95], v[198:201], v[96:99], v[80:95]
	v_pk_add_f32 v[190:191], v[190:191], v[132:133]
	v_exp_f32_e32 v127, v127
	v_exp_f32_e32 v134, v134
	v_pk_add_f32 v[190:191], v[190:191], v[128:129]
	v_exp_f32_e32 v135, v135
	s_waitcnt lgkmcnt(0)
	v_mfma_f32_32x32x16_bf16 v[64:79], v[202:205], v[96:99], v[64:79]
	ds_read_b128 v[198:201], v176 offset:40960
	ds_read_b128 v[202:205], v176 offset:45056
	v_exp_f32_e32 v130, v130
	v_pk_add_f32 v[190:191], v[190:191], v[126:127]
	v_exp_f32_e32 v131, v131
	v_exp_f32_e32 v124, v124
	v_pk_add_f32 v[190:191], v[190:191], v[134:135]
	s_waitcnt lgkmcnt(1)
	v_mfma_f32_32x32x16_bf16 v[80:95], v[198:201], v[104:107], v[80:95]
	v_exp_f32_e32 v125, v125
	v_pk_add_f32 v[190:191], v[190:191], v[130:131]
	v_add_f32_e32 v136, v196, v141
	v_pk_add_f32 v[190:191], v[190:191], v[124:125]
	v_add_f32_e32 v190, v190, v191
	v_add_f32_e32 v190, v136, v190
	v_mov_b32_e32 v191, v190
	s_waitcnt lgkmcnt(0)
	v_mfma_f32_32x32x16_bf16 v[64:79], v[202:205], v[104:107], v[64:79]
	v_cvt_pk_bf16_f32 v136, v144, v146
	v_cvt_pk_bf16_f32 v138, v160, v162
	v_cvt_pk_bf16_f32 v142, v142, v143
	v_cvt_pk_bf16_f32 v143, v145, v147
	v_cvt_pk_bf16_f32 v146, v141, v192
	v_cvt_pk_bf16_f32 v147, v194, v195
	v_cvt_pk_bf16_f32 v192, v126, v127
	v_cvt_pk_bf16_f32 v194, v130, v131
	v_permlane32_swap_b32_e32 v190, v191
	v_cvt_pk_bf16_f32 v137, v148, v150
	v_cvt_pk_bf16_f32 v139, v163, v196
	v_permlane32_swap_b32_e32 v136, v138
	v_cvt_pk_bf16_f32 v144, v149, v151
	v_cvt_pk_bf16_f32 v145, v161, v193
	v_cvt_pk_bf16_f32 v148, v132, v133
	v_cvt_pk_bf16_f32 v149, v128, v129
	v_cvt_pk_bf16_f32 v193, v134, v135
	v_cvt_pk_bf16_f32 v195, v124, v125
	v_permlane32_swap_b32_e32 v192, v194
	v_permlane32_swap_b32_e32 v137, v139
	v_permlane32_swap_b32_e32 v142, v144
	v_permlane32_swap_b32_e32 v143, v145
	v_permlane32_swap_b32_e32 v146, v148
	v_permlane32_swap_b32_e32 v147, v149
	v_permlane32_swap_b32_e32 v193, v195
	v_lshl_add_u64 v[160:161], v[158:159], 0, s[30:31]
	v_add_co_u32_e32 v124, vcc, s39, v160
	s_mov_b32 s4, 0x186c0000
	s_nop 0
	v_addc_co_u32_e32 v125, vcc, 0, v161, vcc
	v_add_co_u32_e32 v128, vcc, s4, v160
	v_lshl_add_u64 v[162:163], v[156:157], 0, s[30:31]
	s_nop 0
	v_addc_co_u32_e32 v129, vcc, 0, v161, vcc
	v_add_co_u32_e32 v132, vcc, s39, v162
	global_load_dwordx4 v[124:127], v[124:125], off offset:3072
	s_nop 0
	global_load_dwordx4 v[128:131], v[128:129], off offset:3072
	v_addc_co_u32_e32 v133, vcc, 0, v163, vcc
	global_load_dwordx4 v[132:135], v[132:133], off offset:1536
	ds_read_b64_tr_b16 v[196:197], v175 offset:0
	ds_read_b64_tr_b16 v[198:199], v175 offset:0x800
	ds_read_b64_tr_b16 v[200:201], v175 offset:0x1000
	ds_read_b64_tr_b16 v[202:203], v175 offset:0x1800
	ds_read_b64_tr_b16 v[204:205], v175 offset:0x2000
	ds_read_b64_tr_b16 v[206:207], v175 offset:0x2800
	ds_read_b64_tr_b16 v[208:209], v175 offset:0x3000
	ds_read_b64_tr_b16 v[210:211], v175 offset:0x3800
	s_waitcnt lgkmcnt(0)
	s_nop 0
	v_mfma_f32_32x32x16_bf16 v[0:15], v[136:139], v[196:199], v[0:15]
	ds_read_b64_tr_b16 v[196:197], v175 offset:0x200
	ds_read_b64_tr_b16 v[198:199], v175 offset:0xa00
	v_mfma_f32_32x32x16_bf16 v[0:15], v[142:145], v[200:203], v[0:15]
	ds_read_b64_tr_b16 v[200:201], v175 offset:0x1200
	ds_read_b64_tr_b16 v[202:203], v175 offset:0x1a00
	v_mfma_f32_32x32x16_bf16 v[0:15], v[146:149], v[204:207], v[0:15]
	ds_read_b64_tr_b16 v[204:205], v175 offset:0x2200
	ds_read_b64_tr_b16 v[206:207], v175 offset:0x2a00
	v_mfma_f32_32x32x16_bf16 v[0:15], v[192:195], v[208:211], v[0:15]
	ds_read_b64_tr_b16 v[208:209], v175 offset:0x3200
	ds_read_b64_tr_b16 v[210:211], v175 offset:0x3a00
	s_waitcnt lgkmcnt(0)
	v_mfma_f32_32x32x16_bf16 v[48:63], v[136:139], v[196:199], v[48:63]
	ds_read_b64_tr_b16 v[196:197], v175 offset:0x400
	ds_read_b64_tr_b16 v[198:199], v175 offset:0xc00
	v_mfma_f32_32x32x16_bf16 v[48:63], v[142:145], v[200:203], v[48:63]
	ds_read_b64_tr_b16 v[200:201], v175 offset:0x1400
	ds_read_b64_tr_b16 v[202:203], v175 offset:0x1c00
	v_mfma_f32_32x32x16_bf16 v[48:63], v[146:149], v[204:207], v[48:63]
	ds_read_b64_tr_b16 v[204:205], v175 offset:0x2400
	ds_read_b64_tr_b16 v[206:207], v175 offset:0x2c00
	v_mfma_f32_32x32x16_bf16 v[48:63], v[192:195], v[208:211], v[48:63]
	ds_read_b64_tr_b16 v[208:209], v175 offset:0x3400
	ds_read_b64_tr_b16 v[210:211], v175 offset:0x3c00
	s_waitcnt lgkmcnt(0)
	v_mfma_f32_32x32x16_bf16 v[32:47], v[136:139], v[196:199], v[32:47]
	ds_read_b64_tr_b16 v[196:197], v175 offset:0x600
	ds_read_b64_tr_b16 v[198:199], v175 offset:0xe00
	v_mfma_f32_32x32x16_bf16 v[32:47], v[142:145], v[200:203], v[32:47]
	ds_read_b64_tr_b16 v[200:201], v175 offset:0x1600
	ds_read_b64_tr_b16 v[202:203], v175 offset:0x1e00
	v_mfma_f32_32x32x16_bf16 v[32:47], v[146:149], v[204:207], v[32:47]
	ds_read_b64_tr_b16 v[204:205], v175 offset:0x2600
	ds_read_b64_tr_b16 v[206:207], v175 offset:0x2e00
	v_mfma_f32_32x32x16_bf16 v[32:47], v[192:195], v[208:211], v[32:47]
	ds_read_b64_tr_b16 v[208:209], v175 offset:0x3600
	ds_read_b64_tr_b16 v[210:211], v175 offset:0x3e00
	s_waitcnt lgkmcnt(0)
	v_mfma_f32_32x32x16_bf16 v[16:31], v[136:139], v[196:199], v[16:31]
	v_max_f32_e32 v136, v81, v81
	v_max_f32_e32 v137, v80, v80
	v_max_f32_e32 v136, v137, v136
	v_max3_f32 v136, v136, v82, v83
	v_max3_f32 v136, v136, v84, v85
	v_max3_f32 v136, v136, v86, v87
	v_max3_f32 v136, v136, v88, v89
	v_max3_f32 v136, v136, v90, v91
	v_max3_f32 v136, v136, v92, v93
	v_mfma_f32_32x32x16_bf16 v[16:31], v[142:145], v[200:203], v[16:31]
	v_max3_f32 v136, v136, v94, v95
	v_max3_f32 v136, v136, v64, v65
	v_max3_f32 v136, v136, v66, v67
	v_max3_f32 v136, v136, v68, v69
	v_max3_f32 v136, v136, v70, v71
	v_max3_f32 v136, v136, v72, v73
	v_max3_f32 v136, v136, v74, v75
	v_max3_f32 v136, v136, v76, v77
	v_mfma_f32_32x32x16_bf16 v[16:31], v[146:149], v[204:207], v[16:31]
	v_max3_f32 v136, v136, v78, v79
	v_mov_b32_e32 v137, v136
	s_nop 1
	v_permlane32_swap_b32_e32 v136, v137
	v_max_f32_e32 v137, v137, v137
	v_max_f32_e32 v136, v136, v136
	v_max_f32_e32 v136, v136, v137
	v_sub_f32_e32 v137, v136, v140
	v_cmp_ge_f32_e32 vcc, s38, v137
	v_max_f32_e32 v137, v140, v140
	v_max_f32_e32 v136, v137, v136
	v_mfma_f32_32x32x16_bf16 v[16:31], v[192:195], v[208:211], v[16:31]
	v_sub_f32_e32 v137, v140, v136
	v_mul_f32_e32 v137, 0x3e38aa3b, v137
	v_exp_f32_e32 v137, v137
	s_cmp_eq_u64 vcc, exec
	s_cselect_b64 s[4:5], -1, 0
	s_barrier
	s_waitcnt vmcnt(3)
	v_cndmask_b32_e64 v192, v137, 1.0, s[4:5]
	v_cmp_gt_f32_e32 vcc, 1.0, v192
	s_waitcnt vmcnt(3)
	ds_write_b128 v179, v[112:115]
	ds_write_b128 v180, v[116:119]
	ds_write_b128 v186, v[120:123] offset:32768
	s_cbranch_vccz .LBB0_1089
	s_and_saveexec_b64 s[8:9], s[6:7]
	ds_write_b32 v155, v192 offset:49280
	s_or_b64 exec, exec, s[8:9]
	s_waitcnt lgkmcnt(0)
	v_add_u32_e32 v137, v153, v178
	ds_read_b128 v[142:145], v137 offset:49376
	ds_read_b128 v[146:149], v137 offset:49344
	ds_read_b128 v[194:197], v137 offset:49312
	ds_read_b128 v[198:201], v137 offset:49280
	s_waitcnt lgkmcnt(3)
	v_pk_mul_f32 v[12:13], v[12:13], v[142:143]
	s_waitcnt lgkmcnt(2)
	v_pk_mul_f32 v[8:9], v[8:9], v[146:147]
	s_waitcnt lgkmcnt(1)
	v_pk_mul_f32 v[4:5], v[4:5], v[194:195]
	v_pk_mul_f32 v[14:15], v[14:15], v[144:145]
	v_pk_mul_f32 v[10:11], v[10:11], v[148:149]
	v_pk_mul_f32 v[6:7], v[6:7], v[196:197]
	s_waitcnt lgkmcnt(0)
	v_pk_mul_f32 v[2:3], v[2:3], v[200:201]
	v_pk_mul_f32 v[0:1], v[0:1], v[198:199]
	v_pk_mul_f32 v[60:61], v[60:61], v[142:143]
	v_pk_mul_f32 v[56:57], v[56:57], v[146:147]
	v_pk_mul_f32 v[52:53], v[52:53], v[194:195]
	v_pk_mul_f32 v[62:63], v[62:63], v[144:145]
	v_pk_mul_f32 v[58:59], v[58:59], v[148:149]
	v_pk_mul_f32 v[54:55], v[54:55], v[196:197]
	v_pk_mul_f32 v[50:51], v[50:51], v[200:201]
	v_pk_mul_f32 v[48:49], v[48:49], v[198:199]
	v_pk_mul_f32 v[44:45], v[44:45], v[142:143]
	v_pk_mul_f32 v[40:41], v[40:41], v[146:147]
	v_pk_mul_f32 v[36:37], v[36:37], v[194:195]
	v_pk_mul_f32 v[46:47], v[46:47], v[144:145]
	v_pk_mul_f32 v[42:43], v[42:43], v[148:149]
	v_pk_mul_f32 v[38:39], v[38:39], v[196:197]
	v_pk_mul_f32 v[34:35], v[34:35], v[200:201]
	v_pk_mul_f32 v[32:33], v[32:33], v[198:199]
	v_pk_mul_f32 v[28:29], v[28:29], v[142:143]
	v_pk_mul_f32 v[24:25], v[24:25], v[146:147]
	v_pk_mul_f32 v[20:21], v[20:21], v[194:195]
	v_pk_mul_f32 v[30:31], v[30:31], v[144:145]
	v_pk_mul_f32 v[26:27], v[26:27], v[148:149]
	v_pk_mul_f32 v[22:23], v[22:23], v[196:197]
	v_pk_mul_f32 v[18:19], v[18:19], v[200:201]
	v_pk_mul_f32 v[16:17], v[16:17], v[198:199]
.LBB0_1089:
	v_cndmask_b32_e64 v193, v136, v140, s[4:5]
	v_mul_f32_e32 v194, 0xbe38aa3b, v193
	v_pk_fma_f32 v[80:81], v[80:81], s[44:45], v[194:195] op_sel_hi:[1,0,0]
	v_pk_fma_f32 v[82:83], v[82:83], s[44:45], v[194:195] op_sel_hi:[1,0,0]
	v_pk_fma_f32 v[84:85], v[84:85], s[44:45], v[194:195] op_sel_hi:[1,0,0]
	v_pk_fma_f32 v[86:87], v[86:87], s[44:45], v[194:195] op_sel_hi:[1,0,0]
	v_pk_fma_f32 v[88:89], v[88:89], s[44:45], v[194:195] op_sel_hi:[1,0,0]
	v_pk_fma_f32 v[90:91], v[90:91], s[44:45], v[194:195] op_sel_hi:[1,0,0]
	v_pk_fma_f32 v[92:93], v[92:93], s[44:45], v[194:195] op_sel_hi:[1,0,0]
	v_pk_fma_f32 v[94:95], v[94:95], s[44:45], v[194:195] op_sel_hi:[1,0,0]
	v_exp_f32_e32 v136, v80
	v_exp_f32_e32 v137, v81
	v_exp_f32_e32 v138, v82
	v_exp_f32_e32 v139, v83
	v_exp_f32_e32 v147, v84
	v_exp_f32_e32 v149, v85
	v_exp_f32_e32 v150, v86
	v_exp_f32_e32 v151, v87
	v_exp_f32_e32 v140, v88
	v_exp_f32_e32 v141, v89
	v_exp_f32_e32 v142, v90
	v_exp_f32_e32 v143, v91
	v_exp_f32_e32 v144, v92
	v_exp_f32_e32 v145, v93
	v_exp_f32_e32 v146, v94
	v_exp_f32_e32 v148, v95
	v_fmamk_f32 v203, v64, 0x3e38aa3b, v194
	v_fmamk_f32 v204, v65, 0x3e38aa3b, v194
	v_fmamk_f32 v205, v66, 0x3e38aa3b, v194
	v_fmamk_f32 v206, v67, 0x3e38aa3b, v194
	v_fmamk_f32 v207, v68, 0x3e38aa3b, v194
	v_fmamk_f32 v196, v69, 0x3e38aa3b, v194
	v_fmamk_f32 v197, v70, 0x3e38aa3b, v194
	v_fmamk_f32 v198, v71, 0x3e38aa3b, v194
	v_fmamk_f32 v199, v72, 0x3e38aa3b, v194
	v_fmamk_f32 v200, v73, 0x3e38aa3b, v194
	v_fmamk_f32 v201, v74, 0x3e38aa3b, v194
	v_fmamk_f32 v202, v75, 0x3e38aa3b, v194
	v_fmamk_f32 v195, v76, 0x3e38aa3b, v194
	v_fmamk_f32 v208, v77, 0x3e38aa3b, v194
	v_fmamk_f32 v209, v78, 0x3e38aa3b, v194
	v_fmac_f32_e32 v194, 0x3e38aa3b, v79
	s_waitcnt lgkmcnt(0)
	s_barrier
	ds_read_b128 v[64:67], v181 offset:32768
	ds_read_b128 v[68:71], v181 offset:36864
	ds_read_b128 v[210:213], v187 offset:32768
	ds_read_b128 v[232:235], v187 offset:36864
	v_exp_f32_e32 v203, v203
	v_exp_f32_e32 v204, v204
	s_waitcnt lgkmcnt(3)
	v_mfma_f32_32x32x16_bf16 v[80:95], v[64:67], v[108:111], 0
	v_exp_f32_e32 v205, v205
	v_exp_f32_e32 v206, v206
	v_exp_f32_e32 v207, v207
	v_exp_f32_e32 v196, v196
	v_exp_f32_e32 v197, v197
	v_exp_f32_e32 v198, v198
	v_exp_f32_e32 v199, v199
	s_waitcnt lgkmcnt(2)
	v_mfma_f32_32x32x16_bf16 v[64:79], v[68:71], v[108:111], 0
	v_exp_f32_e32 v200, v200
	v_exp_f32_e32 v201, v201
	v_exp_f32_e32 v202, v202
	v_exp_f32_e32 v208, v208
	v_exp_f32_e32 v209, v209
	s_waitcnt lgkmcnt(1)
	v_mfma_f32_32x32x16_bf16 v[80:95], v[210:213], v[100:103], v[80:95]
	s_waitcnt lgkmcnt(0)
	v_mfma_f32_32x32x16_bf16 v[64:79], v[232:235], v[100:103], v[64:79]
	ds_read_b128 v[210:213], v188 offset:32768
	ds_read_b128 v[232:235], v188 offset:36864
	s_waitcnt lgkmcnt(1)
	v_mfma_f32_32x32x16_bf16 v[80:95], v[210:213], v[96:99], v[80:95]
	s_waitcnt lgkmcnt(0)
	v_mfma_f32_32x32x16_bf16 v[64:79], v[232:235], v[96:99], v[64:79]
	ds_read_b128 v[210:213], v176 offset:32768
	ds_read_b128 v[232:235], v176 offset:36864
	s_waitcnt lgkmcnt(1)
	v_mfma_f32_32x32x16_bf16 v[80:95], v[210:213], v[104:107], v[80:95]
	v_exp_f32_e32 v211, v194
	v_exp_f32_e32 v210, v195
	s_nop 0
	v_pk_add_f32 v[194:195], v[136:137], v[138:139]
	v_pk_add_f32 v[194:195], v[194:195], v[146:147]
	v_pk_add_f32 v[194:195], v[194:195], v[148:149]
	v_pk_add_f32 v[194:195], v[194:195], v[150:151]
	v_pk_add_f32 v[194:195], v[194:195], v[140:141]
	v_pk_add_f32 v[194:195], v[194:195], v[142:143]
	v_pk_add_f32 v[194:195], v[194:195], v[144:145]
	v_pk_add_f32 v[194:195], v[194:195], v[196:197]
	v_pk_add_f32 v[194:195], v[194:195], v[198:199]
	s_waitcnt lgkmcnt(0)
	v_mfma_f32_32x32x16_bf16 v[64:79], v[232:235], v[104:107], v[64:79]
	v_pk_add_f32 v[194:195], v[194:195], v[200:201]
	v_pk_add_f32 v[194:195], v[194:195], v[202:203]
	v_pk_add_f32 v[194:195], v[194:195], v[204:205]
	v_pk_add_f32 v[194:195], v[194:195], v[206:207]
	v_pk_add_f32 v[194:195], v[194:195], v[208:209]
	v_pk_add_f32 v[194:195], v[194:195], v[210:211]
	v_add_f32_e32 v194, v194, v195
	v_mov_b32_e32 v195, v194
	v_cvt_pk_bf16_f32 v136, v136, v137
	v_cvt_pk_bf16_f32 v137, v138, v139
	v_cvt_pk_bf16_f32 v138, v147, v149
	v_cvt_pk_bf16_f32 v139, v150, v151
	v_cvt_pk_bf16_f32 v140, v140, v141
	v_cvt_pk_bf16_f32 v141, v142, v143
	v_cvt_pk_bf16_f32 v142, v144, v145
	v_cvt_pk_bf16_f32 v143, v146, v148
	v_cvt_pk_bf16_f32 v144, v203, v204
	v_cvt_pk_bf16_f32 v145, v205, v206
	v_cvt_pk_bf16_f32 v146, v207, v196
	v_cvt_pk_bf16_f32 v147, v197, v198
	v_cvt_pk_bf16_f32 v148, v199, v200
	v_cvt_pk_bf16_f32 v149, v201, v202
	v_cvt_pk_bf16_f32 v150, v210, v208
	v_cvt_pk_bf16_f32 v151, v209, v211
	v_permlane32_swap_b32_e32 v194, v195
	v_permlane32_swap_b32_e32 v136, v138
	v_permlane32_swap_b32_e32 v137, v139
	v_permlane32_swap_b32_e32 v140, v142
	v_permlane32_swap_b32_e32 v141, v143
	v_permlane32_swap_b32_e32 v144, v146
	v_permlane32_swap_b32_e32 v145, v147
	v_permlane32_swap_b32_e32 v148, v150
	v_permlane32_swap_b32_e32 v149, v151
	s_cmp_ge_u32 s46, s47
	s_cselect_b64 s[8:9], -1, 0
	s_and_b64 vcc, exec, s[8:9]
	s_cbranch_vccnz .LBB0_1091
	v_add_co_u32_e32 v112, vcc, 0x18700000, v160
	s_nop 1
	v_addc_co_u32_e32 v113, vcc, 0, v161, vcc
	v_add_co_u32_e32 v116, vcc, 0x18740000, v160
	s_nop 1
	v_addc_co_u32_e32 v117, vcc, 0, v161, vcc
	v_add_co_u32_e32 v120, vcc, 0x18700000, v162
	global_load_dwordx4 v[112:115], v[112:113], off offset:3072
	s_nop 0
	global_load_dwordx4 v[116:119], v[116:117], off offset:3072
	v_addc_co_u32_e32 v121, vcc, 0, v163, vcc
	global_load_dwordx4 v[120:123], v[120:121], off offset:1536

.LBB0_1095:
	v_cndmask_b32_e64 v140, v136, v193, s[4:5]
	v_mul_f32_e32 v124, 0xbe38aa3b, v140
	v_pk_fma_f32 v[80:81], v[80:81], s[44:45], v[124:125] op_sel_hi:[1,0,0]
	v_pk_fma_f32 v[82:83], v[82:83], s[44:45], v[124:125] op_sel_hi:[1,0,0]
	v_pk_fma_f32 v[84:85], v[84:85], s[44:45], v[124:125] op_sel_hi:[1,0,0]
	v_pk_fma_f32 v[86:87], v[86:87], s[44:45], v[124:125] op_sel_hi:[1,0,0]
	v_pk_fma_f32 v[88:89], v[88:89], s[44:45], v[124:125] op_sel_hi:[1,0,0]
	v_pk_fma_f32 v[90:91], v[90:91], s[44:45], v[124:125] op_sel_hi:[1,0,0]
	v_pk_fma_f32 v[92:93], v[92:93], s[44:45], v[124:125] op_sel_hi:[1,0,0]
	v_pk_fma_f32 v[94:95], v[94:95], s[44:45], v[124:125] op_sel_hi:[1,0,0]
	v_exp_f32_e32 v144, v80
	v_exp_f32_e32 v146, v81
	v_exp_f32_e32 v148, v82
	v_exp_f32_e32 v150, v83
	v_exp_f32_e32 v160, v84
	v_exp_f32_e32 v162, v85
	v_exp_f32_e32 v163, v86
	v_exp_f32_e32 v196, v87
	v_exp_f32_e32 v142, v88
	v_exp_f32_e32 v143, v89
	v_exp_f32_e32 v145, v90
	v_exp_f32_e32 v147, v91
	v_exp_f32_e32 v149, v92
	v_exp_f32_e32 v151, v93
	v_exp_f32_e32 v161, v94
	v_exp_f32_e32 v193, v95
	v_pk_fma_f32 v[138:139], v[64:65], s[44:45], v[124:125] op_sel_hi:[1,0,0]
	v_add_f32_e32 v64, v190, v191
	v_fmac_f32_e32 v64, v189, v173
	v_add_f32_e32 v173, v194, v195
	v_pk_fma_f32 v[136:137], v[66:67], s[44:45], v[124:125] op_sel_hi:[1,0,0]
	v_pk_fma_f32 v[132:133], v[68:69], s[44:45], v[124:125] op_sel_hi:[1,0,0]
	v_pk_fma_f32 v[128:129], v[70:71], s[44:45], v[124:125] op_sel_hi:[1,0,0]
	v_pk_fma_f32 v[126:127], v[72:73], s[44:45], v[124:125] op_sel_hi:[1,0,0]
	v_pk_fma_f32 v[134:135], v[74:75], s[44:45], v[124:125] op_sel_hi:[1,0,0]
	v_pk_fma_f32 v[130:131], v[76:77], s[44:45], v[124:125] op_sel_hi:[1,0,0]
	v_pk_fma_f32 v[124:125], v[78:79], s[44:45], v[124:125] op_sel_hi:[1,0,0]
	v_fmac_f32_e32 v173, v64, v192
	v_lshl_add_u64 v[156:157], v[156:157], 0, s[0:1]
	v_lshl_add_u64 v[158:159], v[158:159], 0, s[0:1]
	s_add_i32 s46, s46, 2
	s_and_b64 vcc, exec, s[8:9]
	s_waitcnt lgkmcnt(0)
	s_barrier
	s_cbranch_vccnz .LBB0_1097
	v_mov_b32_e32 v189, v141
	s_branch .LBB0_1085
